# mixers loops: v_mov+v_pk_add row-sum shuffles and all v_pk_add_f32 unpacked to plain v_add_f32
# baseline (speedup 1.0000x reference)
.LBB0_1561:
	v_exp_f32_e32 v64, v64
	v_exp_f32_e32 v65, v65
	v_exp_f32_e32 v66, v66
	v_exp_f32_e32 v67, v67
	v_exp_f32_e32 v68, v68
	v_exp_f32_e32 v120, v52
	v_exp_f32_e32 v69, v69
	v_exp_f32_e32 v121, v53
	v_exp_f32_e32 v52, v70
	v_exp_f32_e32 v53, v71
	v_exp_f32_e32 v116, v48
	v_exp_f32_e32 v117, v49
	v_exp_f32_e32 v118, v50
	v_exp_f32_e32 v119, v51
	v_cvt_pk_bf16_f32 v48, v64, v65
	v_cvt_pk_bf16_f32 v49, v66, v67
	v_cvt_pk_bf16_f32 v50, v68, v69
	v_cvt_pk_bf16_f32 v51, v52, v53
	v_exp_f32_e32 v70, v54
	v_exp_f32_e32 v71, v55
	v_mfma_f32_32x32x16_bf16 v[32:47], v[88:91], v[48:51], v[32:47]
	v_exp_f32_e32 v54, v72
	v_exp_f32_e32 v55, v73
	v_exp_f32_e32 v72, v74
	v_exp_f32_e32 v73, v75
	v_exp_f32_e32 v74, v76
	v_exp_f32_e32 v75, v77
	v_exp_f32_e32 v76, v78
	v_mfma_f32_32x32x16_bf16 v[16:31], v[84:87], v[48:51], v[16:31]
	v_exp_f32_e32 v77, v79
	v_exp_f32_e32 v58, v58
	v_exp_f32_e32 v59, v59
	v_exp_f32_e32 v56, v56
	v_exp_f32_e32 v57, v57
	v_cvt_pk_bf16_f32 v48, v54, v55
	v_cvt_pk_bf16_f32 v49, v72, v73
	v_cvt_pk_bf16_f32 v50, v74, v75
	v_cvt_pk_bf16_f32 v51, v76, v77
	v_add_f32_e32 v78, v70, v52
	v_add_f32_e32 v79, v71, v53
	v_add_f32_e32 v52, v118, v66
	v_add_f32_e32 v53, v119, v67
	v_mfma_f32_32x32x16_bf16 v[32:47], v[80:83], v[48:51], v[32:47]
	v_add_f32_e64 v66, v58, v72
	v_add_f32_e64 v67, v59, v73
	v_add_f32_e64 v122, v56, v54
	v_add_f32_e64 v123, v57, v55
	v_add_f32_e32 v67, v66, v67
	v_add_f32_e32 v66, v52, v53
	ds_read_b64_tr_b16 v[52:53], v115 offset:23040
	ds_read_b64_tr_b16 v[54:55], v115 offset:24192
	v_mfma_f32_32x32x16_bf16 v[16:31], v[10:13], v[48:51], v[16:31]
	ds_read_b64_tr_b16 v[50:51], v115 offset:24256
	ds_read_b64_tr_b16 v[48:49], v115 offset:23104
	v_exp_f32_e32 v60, v60
	v_exp_f32_e32 v61, v61
	v_cvt_pk_bf16_f32 v10, v116, v117
	v_cvt_pk_bf16_f32 v11, v118, v119
	v_cvt_pk_bf16_f32 v12, v120, v121
	v_cvt_pk_bf16_f32 v13, v70, v71
	v_add_f32_e32 v64, v116, v64
	v_add_f32_e32 v65, v117, v65
	v_add_f32_e32 v68, v120, v68
	v_add_f32_e32 v69, v121, v69
	s_waitcnt lgkmcnt(2)
	v_mfma_f32_32x32x16_bf16 v[32:47], v[52:55], v[10:13], v[32:47]
	v_add_f32_e64 v90, v60, v74
	v_add_f32_e64 v91, v61, v75
	v_add_f32_e32 v64, v64, v65
	v_add_f32_e32 v65, v122, v123
	s_waitcnt lgkmcnt(0)
	v_mfma_f32_32x32x16_bf16 v[16:31], v[48:51], v[10:13], v[16:31]
	v_exp_f32_e32 v62, v62
	v_exp_f32_e32 v63, v63
	v_add_f32_e32 v64, v64, v66
	v_add_f32_e32 v65, v65, v67
	v_add_f32_e32 v67, v90, v91
	v_add_f32_e32 v66, v68, v69
	ds_read_b64_tr_b16 v[52:53], v115 offset:25344
	ds_read_b64_tr_b16 v[54:55], v115 offset:26496
	ds_read_b64_tr_b16 v[50:51], v115 offset:26560
	ds_read_b64_tr_b16 v[48:49], v115 offset:25408
	v_cvt_pk_bf16_f32 v10, v56, v57
	v_cvt_pk_bf16_f32 v11, v58, v59
	v_cvt_pk_bf16_f32 v12, v60, v61
	v_cvt_pk_bf16_f32 v13, v62, v63
	v_add_f32_e32 v88, v62, v76
	v_add_f32_e32 v89, v63, v77
	v_mov_b32_e32 v68, v78
	s_waitcnt lgkmcnt(2)
	v_mfma_f32_32x32x16_bf16 v[32:47], v[52:55], v[10:13], v[32:47]
	v_mov_b32_e32 v69, v88
	v_mov_b32_e32 v88, v79
	v_add_f32_e64 v52, v68, v88
	v_add_f32_e64 v53, v69, v89
	s_add_i32 s7, s7, 1
	v_add_f32_e32 v52, v66, v52
	v_add_f32_e32 v53, v67, v53
	s_mov_b64 s[12:13], 0x2000
	s_waitcnt lgkmcnt(0)
	v_mfma_f32_32x32x16_bf16 v[16:31], v[48:51], v[10:13], v[16:31]
	v_add_f32_e64 v52, v64, v52
	v_add_f32_e64 v53, v65, v53
	s_addk_i32 s10, 0x400
	v_add_f32_e32 v52, v52, v53
	v_add_f32_e32 v15, v15, v52
	v_lshl_add_u64 v[94:95], v[94:95], 0, s[12:13]
	s_cmp_lg_u32 s6, s7
	v_lshl_add_u64 v[96:97], v[96:97], 0, s[12:13]
	s_cbranch_scc0 .LBB0_1571

.LBB0_1650:
	v_exp_f32_e32 v96, v96
	v_exp_f32_e32 v97, v97
	v_exp_f32_e32 v98, v98
	v_exp_f32_e32 v99, v99
	v_exp_f32_e32 v100, v100
	v_exp_f32_e32 v136, v84
	v_exp_f32_e32 v101, v101
	v_exp_f32_e32 v137, v85
	v_exp_f32_e32 v84, v102
	v_exp_f32_e32 v85, v103
	v_exp_f32_e32 v132, v80
	v_exp_f32_e32 v133, v81
	v_exp_f32_e32 v134, v82
	v_exp_f32_e32 v135, v83
	v_cvt_pk_bf16_f32 v80, v96, v97
	v_cvt_pk_bf16_f32 v81, v98, v99
	v_cvt_pk_bf16_f32 v82, v100, v101
	v_cvt_pk_bf16_f32 v83, v84, v85
	v_exp_f32_e32 v102, v86
	v_exp_f32_e32 v103, v87
	v_mfma_f32_32x32x16_bf16 v[64:79], v[120:123], v[80:83], v[64:79]
	v_exp_f32_e32 v86, v104
	v_exp_f32_e32 v87, v105
	v_exp_f32_e32 v104, v106
	v_exp_f32_e32 v105, v107
	v_exp_f32_e32 v106, v108
	v_exp_f32_e32 v107, v109
	v_exp_f32_e32 v108, v110
	v_mfma_f32_32x32x16_bf16 v[48:63], v[116:119], v[80:83], v[48:63]
	v_exp_f32_e32 v109, v111
	v_exp_f32_e32 v90, v90
	v_exp_f32_e32 v91, v91
	v_exp_f32_e32 v88, v88
	v_exp_f32_e32 v89, v89
	v_cvt_pk_bf16_f32 v80, v86, v87
	v_cvt_pk_bf16_f32 v81, v104, v105
	v_cvt_pk_bf16_f32 v82, v106, v107
	v_cvt_pk_bf16_f32 v83, v108, v109
	v_add_f32_e32 v110, v102, v84
	v_add_f32_e32 v111, v103, v85
	v_add_f32_e32 v84, v134, v98
	v_add_f32_e32 v85, v135, v99
	v_mfma_f32_32x32x16_bf16 v[64:79], v[112:115], v[80:83], v[64:79]
	v_add_f32_e64 v98, v90, v104
	v_add_f32_e64 v99, v91, v105
	v_add_f32_e64 v138, v88, v86
	v_add_f32_e64 v139, v89, v87
	v_add_f32_e32 v99, v98, v99
	v_add_f32_e32 v98, v84, v85
	ds_read_b64_tr_b16 v[84:85], v131 offset:23040
	ds_read_b64_tr_b16 v[86:87], v131 offset:24192
	v_mfma_f32_32x32x16_bf16 v[48:63], v[10:13], v[80:83], v[48:63]
	ds_read_b64_tr_b16 v[82:83], v131 offset:24256
	ds_read_b64_tr_b16 v[80:81], v131 offset:23104
	v_exp_f32_e32 v92, v92
	v_exp_f32_e32 v93, v93
	v_cvt_pk_bf16_f32 v10, v132, v133
	v_cvt_pk_bf16_f32 v11, v134, v135
	v_cvt_pk_bf16_f32 v12, v136, v137
	v_cvt_pk_bf16_f32 v13, v102, v103
	v_add_f32_e32 v96, v132, v96
	v_add_f32_e32 v97, v133, v97
	v_add_f32_e32 v100, v136, v100
	v_add_f32_e32 v101, v137, v101
	s_waitcnt lgkmcnt(2)
	v_mfma_f32_32x32x16_bf16 v[64:79], v[84:87], v[10:13], v[64:79]
	v_add_f32_e64 v122, v92, v106
	v_add_f32_e64 v123, v93, v107
	v_add_f32_e32 v96, v96, v97
	v_add_f32_e32 v97, v138, v139
	s_waitcnt lgkmcnt(0)
	v_mfma_f32_32x32x16_bf16 v[48:63], v[80:83], v[10:13], v[48:63]
	v_exp_f32_e32 v94, v94
	v_exp_f32_e32 v95, v95
	v_add_f32_e32 v96, v96, v98
	v_add_f32_e32 v97, v97, v99
	v_add_f32_e32 v99, v122, v123
	v_add_f32_e32 v98, v100, v101
	ds_read_b64_tr_b16 v[84:85], v131 offset:25344
	ds_read_b64_tr_b16 v[86:87], v131 offset:26496
	ds_read_b64_tr_b16 v[82:83], v131 offset:26560
	ds_read_b64_tr_b16 v[80:81], v131 offset:25408
	v_cvt_pk_bf16_f32 v10, v88, v89
	v_cvt_pk_bf16_f32 v11, v90, v91
	v_cvt_pk_bf16_f32 v12, v92, v93
	v_cvt_pk_bf16_f32 v13, v94, v95
	v_add_f32_e32 v120, v94, v108
	v_add_f32_e32 v121, v95, v109
	v_mov_b32_e32 v100, v110
	s_waitcnt lgkmcnt(2)
	v_mfma_f32_32x32x16_bf16 v[64:79], v[84:87], v[10:13], v[64:79]
	v_mov_b32_e32 v101, v120
	v_mov_b32_e32 v120, v111
	v_add_f32_e64 v84, v100, v120
	v_add_f32_e64 v85, v101, v121
	v_add_f32_e64 v84, v98, v84
	v_add_f32_e64 v85, v99, v85
	s_waitcnt lgkmcnt(0)
	v_mfma_f32_32x32x16_bf16 v[48:63], v[80:83], v[10:13], v[48:63]
	v_add_f32_e64 v84, v96, v84
	v_add_f32_e64 v85, v97, v85
	v_add_f32_e32 v84, v84, v85
	v_add_f32_e32 v194, v194, v84

.LBB0_1663:
	v_exp_f32_e32 v128, v128
	v_exp_f32_e32 v129, v129
	v_exp_f32_e32 v130, v130
	v_exp_f32_e32 v131, v131
	v_exp_f32_e32 v132, v132
	v_exp_f32_e32 v180, v116
	v_exp_f32_e32 v133, v133
	v_exp_f32_e32 v181, v117
	v_exp_f32_e32 v116, v134
	v_exp_f32_e32 v117, v135
	v_exp_f32_e32 v176, v112
	v_exp_f32_e32 v177, v113
	v_exp_f32_e32 v178, v114
	v_exp_f32_e32 v179, v115
	v_cvt_pk_bf16_f32 v112, v128, v129
	v_cvt_pk_bf16_f32 v113, v130, v131
	v_cvt_pk_bf16_f32 v114, v132, v133
	v_cvt_pk_bf16_f32 v115, v116, v117
	v_exp_f32_e32 v134, v118
	v_exp_f32_e32 v135, v119
	v_mfma_f32_32x32x16_bf16 v[96:111], v[168:171], v[112:115], v[96:111]
	v_exp_f32_e32 v118, v136
	v_exp_f32_e32 v119, v137
	v_exp_f32_e32 v136, v138
	v_exp_f32_e32 v137, v139
	v_exp_f32_e32 v138, v140
	v_exp_f32_e32 v139, v141
	v_exp_f32_e32 v140, v142
	v_mfma_f32_32x32x16_bf16 v[80:95], v[164:167], v[112:115], v[80:95]
	v_exp_f32_e32 v141, v143
	v_exp_f32_e32 v122, v122
	v_exp_f32_e32 v123, v123
	v_exp_f32_e32 v120, v120
	v_exp_f32_e32 v121, v121
	v_cvt_pk_bf16_f32 v112, v118, v119
	v_cvt_pk_bf16_f32 v113, v136, v137
	v_cvt_pk_bf16_f32 v114, v138, v139
	v_cvt_pk_bf16_f32 v115, v140, v141
	v_add_f32_e32 v142, v134, v116
	v_add_f32_e32 v143, v135, v117
	v_add_f32_e32 v116, v178, v130
	v_add_f32_e32 v117, v179, v131
	v_mfma_f32_32x32x16_bf16 v[96:111], v[160:163], v[112:115], v[96:111]
	v_add_f32_e64 v130, v122, v136
	v_add_f32_e64 v131, v123, v137
	v_add_f32_e64 v182, v120, v118
	v_add_f32_e64 v183, v121, v119
	v_add_f32_e32 v131, v130, v131
	v_add_f32_e32 v130, v116, v117
	ds_read_b64_tr_b16 v[116:117], v205 offset:23040
	ds_read_b64_tr_b16 v[118:119], v205 offset:24192
	v_mfma_f32_32x32x16_bf16 v[80:95], v[10:13], v[112:115], v[80:95]
	ds_read_b64_tr_b16 v[114:115], v205 offset:24256
	ds_read_b64_tr_b16 v[112:113], v205 offset:23104
	v_exp_f32_e32 v124, v124
	v_exp_f32_e32 v125, v125
	v_cvt_pk_bf16_f32 v10, v176, v177
	v_cvt_pk_bf16_f32 v11, v178, v179
	v_cvt_pk_bf16_f32 v12, v180, v181
	v_cvt_pk_bf16_f32 v13, v134, v135
	v_add_f32_e32 v128, v176, v128
	v_add_f32_e32 v129, v177, v129
	v_add_f32_e32 v132, v180, v132
	v_add_f32_e32 v133, v181, v133
	s_waitcnt lgkmcnt(2)
	v_mfma_f32_32x32x16_bf16 v[96:111], v[116:119], v[10:13], v[96:111]
	v_add_f32_e64 v170, v124, v138
	v_add_f32_e64 v171, v125, v139
	v_add_f32_e32 v128, v128, v129
	v_add_f32_e32 v129, v182, v183
	s_waitcnt lgkmcnt(0)
	v_mfma_f32_32x32x16_bf16 v[80:95], v[112:115], v[10:13], v[80:95]
	v_exp_f32_e32 v126, v126
	v_exp_f32_e32 v127, v127
	v_add_f32_e32 v128, v128, v130
	v_add_f32_e32 v129, v129, v131
	v_add_f32_e32 v131, v170, v171
	v_add_f32_e32 v130, v132, v133
	ds_read_b64_tr_b16 v[116:117], v205 offset:25344
	ds_read_b64_tr_b16 v[118:119], v205 offset:26496
	ds_read_b64_tr_b16 v[114:115], v205 offset:26560
	ds_read_b64_tr_b16 v[112:113], v205 offset:25408
	v_cvt_pk_bf16_f32 v10, v120, v121
	v_cvt_pk_bf16_f32 v11, v122, v123
	v_cvt_pk_bf16_f32 v12, v124, v125
	v_cvt_pk_bf16_f32 v13, v126, v127
	v_add_f32_e32 v168, v126, v140
	v_add_f32_e32 v169, v127, v141
	v_mov_b32_e32 v132, v142
	s_waitcnt lgkmcnt(2)
	v_mfma_f32_32x32x16_bf16 v[96:111], v[116:119], v[10:13], v[96:111]
	v_mov_b32_e32 v133, v168
	v_mov_b32_e32 v168, v143
	v_add_f32_e64 v116, v132, v168
	v_add_f32_e64 v117, v133, v169
	s_add_i32 s4, s4, 1
	v_add_f32_e32 v116, v130, v116
	v_add_f32_e32 v117, v131, v117
	s_add_i32 s0, s2, s4
	s_waitcnt lgkmcnt(0)
	v_mfma_f32_32x32x16_bf16 v[80:95], v[112:115], v[10:13], v[80:95]
	v_add_f32_e64 v116, v128, v116
	v_add_f32_e64 v117, v129, v117
	s_add_i32 s0, s0, -9
	v_add_f32_e32 v116, v116, v117
	v_add_f32_e32 v196, v196, v116
	s_cmp_lt_i32 s0, s76
	v_add_u32_e32 v203, 64, v203
	s_cbranch_scc0 .LBB0_1670

.LBB0_1701:
	v_exp_f32_e32 v78, v0
	v_exp_f32_e32 v79, v53
	v_exp_f32_e32 v132, v2
	v_exp_f32_e32 v133, v3
	v_exp_f32_e32 v134, v4
	v_exp_f32_e32 v135, v5
	v_exp_f32_e32 v6, v6
	v_exp_f32_e32 v7, v7
	v_cvt_pk_bf16_f32 v2, v78, v79
	v_cvt_pk_bf16_f32 v3, v132, v133
	v_cvt_pk_bf16_f32 v4, v134, v135
	v_cvt_pk_bf16_f32 v5, v6, v7
	v_exp_f32_e32 v8, v8
	v_exp_f32_e32 v9, v9
	v_mfma_f32_32x32x16_bf16 v[32:47], v[104:107], v[2:5], v[32:47]
	v_exp_f32_e32 v10, v10
	v_exp_f32_e32 v11, v11
	v_exp_f32_e32 v12, v12
	v_exp_f32_e32 v13, v13
	v_exp_f32_e32 v14, v14
	v_exp_f32_e32 v15, v15
	v_exp_f32_e32 v130, v62
	v_mfma_f32_32x32x16_bf16 v[16:31], v[74:77], v[2:5], v[16:31]
	v_exp_f32_e32 v131, v65
	v_exp_f32_e32 v62, v60
	v_exp_f32_e32 v63, v63
	v_exp_f32_e32 v60, v58
	v_exp_f32_e32 v58, v56
	v_exp_f32_e32 v59, v59
	v_exp_f32_e32 v56, v54
	v_exp_f32_e32 v57, v57
	v_exp_f32_e32 v52, v52
	v_exp_f32_e32 v53, v55
	v_exp_f32_e32 v61, v61
	v_exp_f32_e32 v50, v50
	v_exp_f32_e32 v51, v51
	v_exp_f32_e32 v48, v48
	v_exp_f32_e32 v49, v49
	v_cvt_pk_bf16_f32 v2, v8, v9
	v_cvt_pk_bf16_f32 v3, v10, v11
	v_cvt_pk_bf16_f32 v4, v12, v13
	v_cvt_pk_bf16_f32 v5, v14, v15
	v_add_f32_e32 v54, v58, v6
	v_add_f32_e32 v55, v59, v7
	v_add_f32_e32 v6, v62, v132
	v_add_f32_e32 v7, v63, v133
	v_add_f32_e32 v132, v52, v10
	v_add_f32_e32 v133, v53, v11
	v_add_f32_e32 v78, v130, v78
	v_add_f32_e32 v79, v131, v79
	v_add_f32_e32 v136, v56, v8
	v_add_f32_e32 v137, v57, v9
	v_mfma_f32_32x32x16_bf16 v[32:47], v[70:73], v[2:5], v[32:47]
	v_mov_b32_e32 v74, v78
	v_mov_b32_e32 v75, v136
	v_mov_b32_e32 v136, v79
	v_mov_b32_e32 v8, v6
	v_mov_b32_e32 v9, v132
	v_mov_b32_e32 v132, v7
	v_add_f32_e32 v106, v60, v134
	v_add_f32_e32 v107, v61, v135
	v_mfma_f32_32x32x16_bf16 v[16:31], v[66:69], v[2:5], v[16:31]
	v_add_f32_e64 v134, v50, v12
	v_add_f32_e64 v135, v51, v13
	v_add_f32_e64 v10, v74, v136
	v_add_f32_e64 v11, v75, v137
	v_add_f32_e64 v12, v8, v132
	v_add_f32_e64 v13, v9, v133
	v_add_f32_e32 v104, v48, v14
	v_add_f32_e32 v105, v49, v15
	ds_read_b64_tr_b16 v[6:7], v64 offset:23040
	ds_read_b64_tr_b16 v[8:9], v64 offset:24192
	v_add_f32_e32 v14, v10, v12
	v_add_f32_e32 v15, v11, v13
	ds_read_b64_tr_b16 v[12:13], v64 offset:24256
	ds_read_b64_tr_b16 v[10:11], v64 offset:23104
	v_cvt_pk_bf16_f32 v2, v130, v131
	v_cvt_pk_bf16_f32 v3, v62, v63
	v_cvt_pk_bf16_f32 v4, v60, v61
	v_cvt_pk_bf16_f32 v5, v58, v59
	v_mov_b32_e32 v60, v54
	v_mov_b32_e32 v61, v104
	s_waitcnt lgkmcnt(2)
	v_mfma_f32_32x32x16_bf16 v[32:47], v[6:9], v[2:5], v[32:47]
	v_mov_b32_e32 v6, v106
	v_mov_b32_e32 v7, v134
	v_mov_b32_e32 v134, v107
	v_add_f32_e64 v58, v6, v134
	v_add_f32_e64 v59, v7, v135
	ds_read_b64_tr_b16 v[6:7], v64 offset:25344
	ds_read_b64_tr_b16 v[8:9], v64 offset:26496
	v_mov_b32_e32 v104, v55
	s_waitcnt lgkmcnt(2)
	v_mfma_f32_32x32x16_bf16 v[16:31], v[10:13], v[2:5], v[16:31]
	ds_read_b64_tr_b16 v[12:13], v64 offset:26560
	ds_read_b64_tr_b16 v[10:11], v64 offset:25408
	v_cvt_pk_bf16_f32 v2, v56, v57
	v_cvt_pk_bf16_f32 v3, v52, v53
	v_cvt_pk_bf16_f32 v4, v50, v51
	v_cvt_pk_bf16_f32 v5, v48, v49
	s_waitcnt lgkmcnt(2)
	s_nop 0
	v_mfma_f32_32x32x16_bf16 v[32:47], v[6:9], v[2:5], v[32:47]
	v_add_f32_e64 v6, v60, v104
	v_add_f32_e64 v7, v61, v105
	v_add_f32_e64 v6, v58, v6
	v_add_f32_e64 v7, v59, v7
	v_add_f32_e64 v6, v14, v6
	v_add_f32_e64 v7, v15, v7
	v_add_f32_e32 v0, v6, v7
	s_waitcnt lgkmcnt(0)
	v_mfma_f32_32x32x16_bf16 v[16:31], v[10:13], v[2:5], v[16:31]
	v_add_f32_e32 v129, v129, v0
	v_mov_b32_e32 v0, 0

.LBB0_1745:
	s_or_b64 exec, exec, s[0:1]
	v_exp_f32_e32 v168, v118
	v_exp_f32_e32 v118, v102
	v_exp_f32_e32 v169, v119
	v_exp_f32_e32 v119, v103
	v_exp_f32_e32 v170, v120
	v_exp_f32_e32 v120, v104
	v_exp_f32_e32 v171, v121
	v_exp_f32_e32 v121, v105
	v_exp_f32_e32 v122, v122
	v_exp_f32_e32 v102, v106
	v_exp_f32_e32 v123, v123
	v_exp_f32_e32 v124, v124
	v_exp_f32_e32 v104, v108
	v_exp_f32_e32 v125, v125
	v_exp_f32_e32 v105, v109
	v_exp_f32_e32 v103, v107
	v_exp_f32_e32 v164, v114
	v_exp_f32_e32 v114, v98
	v_exp_f32_e32 v165, v115
	v_exp_f32_e32 v115, v99
	v_exp_f32_e32 v166, v116
	v_exp_f32_e32 v116, v100
	v_exp_f32_e32 v167, v117
	v_exp_f32_e32 v117, v101
	v_exp_f32_e32 v162, v126
	v_exp_f32_e32 v98, v110
	v_exp_f32_e32 v163, v127
	v_exp_f32_e32 v126, v128
	v_exp_f32_e32 v100, v112
	v_exp_f32_e32 v127, v129
	v_exp_f32_e32 v101, v113
	v_exp_f32_e32 v99, v111
	v_add_f32_e32 v108, v104, v124
	v_add_f32_e32 v109, v105, v125
	v_add_f32_e32 v112, v102, v122
	v_add_f32_e32 v113, v103, v123
	v_add_f32_e32 v110, v100, v126
	v_add_f32_e32 v111, v101, v127
	v_add_f32_e32 v106, v98, v162
	v_add_f32_e32 v107, v99, v163
	v_add_f32_e32 v128, v120, v170
	v_add_f32_e32 v129, v121, v171
	v_add_f32_e32 v176, v118, v168
	v_add_f32_e32 v177, v119, v169
	v_add_f32_e32 v178, v116, v166
	v_add_f32_e32 v179, v117, v167
	v_add_f32_e32 v180, v114, v164
	v_add_f32_e32 v181, v115, v165
	v_add_f32_e32 v112, v112, v113
	v_add_f32_e32 v108, v108, v109
	v_add_f32_e32 v180, v180, v181
	v_add_f32_e32 v178, v178, v179
	v_add_f32_e32 v176, v176, v177
	v_add_f32_e32 v128, v128, v129
	v_add_f32_e32 v129, v112, v108
	v_add_f32_e32 v112, v106, v107
	v_add3_u32 v179, s15, v187, v188
	v_add_f32_e32 v110, v110, v111
	v_add_f32_e32 v178, v180, v178
	v_add_f32_e32 v128, v176, v128
	ds_read_b64_tr_b16 v[106:107], v179 offset:18432
	ds_read_b64_tr_b16 v[108:109], v179 offset:19584
	v_add_f32_e32 v176, v112, v110
	v_cvt_pk_bf16_f32 v110, v164, v165
	v_cvt_pk_bf16_f32 v111, v166, v167
	ds_read_b64_tr_b16 v[166:167], v179 offset:19648
	ds_read_b64_tr_b16 v[164:165], v179 offset:18496
	v_cvt_pk_bf16_f32 v112, v168, v169
	v_cvt_pk_bf16_f32 v113, v170, v171
	v_add_f32_e32 v178, v178, v128
	v_add_f32_e32 v180, v129, v176
	v_exp_f32_e32 v128, v82
	v_exp_f32_e32 v129, v83
	v_exp_f32_e32 v168, v84
	v_exp_f32_e32 v169, v85
	v_exp_f32_e32 v170, v86
	v_exp_f32_e32 v171, v87
	v_exp_f32_e32 v176, v88
	v_exp_f32_e32 v177, v89
	s_waitcnt lgkmcnt(2)
	v_mfma_f32_32x32x16_bf16 v[18:33], v[106:109], v[110:113], v[18:33]
	v_cvt_pk_bf16_f32 v82, v128, v129
	v_cvt_pk_bf16_f32 v83, v168, v169
	v_cvt_pk_bf16_f32 v84, v170, v171
	v_cvt_pk_bf16_f32 v85, v176, v177
	v_exp_f32_e32 v94, v94
	v_exp_f32_e32 v95, v95
	v_exp_f32_e32 v96, v96
	s_waitcnt lgkmcnt(0)
	v_mfma_f32_32x32x16_bf16 v[2:17], v[164:167], v[110:113], v[2:17]
	v_exp_f32_e32 v97, v97
	v_add_f32_e32 v86, v178, v180
	v_add_f32_e32 v189, v189, v86
	v_cvt_pk_bf16_f32 v86, v122, v123
	v_cvt_pk_bf16_f32 v87, v124, v125
	v_cvt_pk_bf16_f32 v88, v162, v163
	v_cvt_pk_bf16_f32 v89, v126, v127
	v_mfma_f32_32x32x16_bf16 v[34:49], v[106:109], v[82:85], v[34:49]
	ds_read_b64_tr_b16 v[106:107], v179 offset:20736
	ds_read_b64_tr_b16 v[108:109], v179 offset:21888
	ds_read_b64_tr_b16 v[112:113], v179 offset:21952
	ds_read_b64_tr_b16 v[110:111], v179 offset:20800
	v_cvt_pk_bf16_f32 v102, v102, v103
	v_cvt_pk_bf16_f32 v103, v104, v105
	v_cvt_pk_bf16_f32 v104, v98, v99
	v_cvt_pk_bf16_f32 v105, v100, v101
	v_exp_f32_e32 v98, v66
	v_mfma_f32_32x32x16_bf16 v[50:65], v[164:167], v[82:85], v[50:65]
	v_cvt_pk_bf16_f32 v82, v114, v115
	v_cvt_pk_bf16_f32 v83, v116, v117
	v_exp_f32_e32 v114, v90
	v_exp_f32_e32 v115, v91
	v_exp_f32_e32 v116, v92
	v_exp_f32_e32 v117, v93
	v_exp_f32_e32 v99, v67
	s_waitcnt lgkmcnt(2)
	v_mfma_f32_32x32x16_bf16 v[18:33], v[106:109], v[86:89], v[18:33]
	v_exp_f32_e32 v100, v68
	ds_read_b64_tr_b16 v[90:91], v179 offset:23040
	ds_read_b64_tr_b16 v[92:93], v179 offset:24192
	v_exp_f32_e32 v101, v69
	ds_read_b64_tr_b16 v[68:69], v179 offset:24256
	ds_read_b64_tr_b16 v[66:67], v179 offset:23104
	v_exp_f32_e32 v78, v78
	v_exp_f32_e32 v79, v79
	v_cvt_pk_bf16_f32 v84, v118, v119
	s_waitcnt lgkmcnt(4)
	v_mfma_f32_32x32x16_bf16 v[2:17], v[110:113], v[86:89], v[2:17]
	v_cvt_pk_bf16_f32 v86, v114, v115
	v_cvt_pk_bf16_f32 v87, v116, v117
	v_cvt_pk_bf16_f32 v88, v94, v95
	v_cvt_pk_bf16_f32 v89, v96, v97
	v_cvt_pk_bf16_f32 v85, v120, v121
	v_exp_f32_e32 v80, v80
	v_exp_f32_e32 v81, v81
	v_mfma_f32_32x32x16_bf16 v[34:49], v[106:109], v[86:89], v[34:49]
	v_exp_f32_e32 v106, v74
	v_exp_f32_e32 v107, v75
	v_exp_f32_e32 v108, v76
	v_exp_f32_e32 v109, v77
	ds_read_b64_tr_b16 v[74:75], v179 offset:25344
	ds_read_b64_tr_b16 v[76:77], v179 offset:26496
	v_mfma_f32_32x32x16_bf16 v[50:65], v[110:113], v[86:89], v[50:65]
	v_exp_f32_e32 v86, v70
	v_exp_f32_e32 v87, v71
	v_exp_f32_e32 v88, v72
	v_exp_f32_e32 v89, v73
	v_cvt_pk_bf16_f32 v70, v98, v99
	v_cvt_pk_bf16_f32 v71, v100, v101
	v_cvt_pk_bf16_f32 v72, v86, v87
	v_cvt_pk_bf16_f32 v73, v88, v89
	s_waitcnt lgkmcnt(4)
	v_mfma_f32_32x32x16_bf16 v[18:33], v[90:93], v[82:85], v[18:33]
	v_add_f32_e64 v86, v86, v170
	v_add_f32_e64 v87, v87, v171
	s_waitcnt lgkmcnt(2)
	v_mfma_f32_32x32x16_bf16 v[2:17], v[66:69], v[82:85], v[2:17]
	v_add_f32_e64 v82, v88, v176
	v_add_f32_e64 v83, v89, v177
	v_add_f32_e64 v88, v78, v94
	v_add_f32_e64 v89, v79, v95
	v_add_f32_e64 v94, v98, v128
	v_add_f32_e64 v95, v99, v129
	v_add_f32_e32 v84, v80, v96
	v_add_f32_e32 v85, v81, v97
	v_mfma_f32_32x32x16_bf16 v[34:49], v[90:93], v[70:73], v[34:49]
	v_add_f32_e64 v90, v100, v168
	v_add_f32_e64 v91, v101, v169
	v_add_f32_e64 v92, v108, v116
	v_add_f32_e64 v93, v109, v117
	v_mfma_f32_32x32x16_bf16 v[50:65], v[66:69], v[70:73], v[50:65]
	v_add_f32_e64 v66, v106, v114
	v_add_f32_e64 v67, v107, v115
	v_add_f32_e32 v70, v94, v95
	v_add_f32_e32 v71, v66, v67
	ds_read_b64_tr_b16 v[68:69], v179 offset:26560
	ds_read_b64_tr_b16 v[66:67], v179 offset:25408
	v_add_f32_e32 v72, v90, v91
	v_add_f32_e32 v73, v92, v93
	s_waitcnt lgkmcnt(2)
	v_mfma_f32_32x32x16_bf16 v[18:33], v[74:77], v[102:105], v[18:33]
	v_add_f32_e64 v90, v70, v72
	v_add_f32_e64 v91, v71, v73
	v_add_f32_e32 v86, v86, v87
	v_add_f32_e32 v87, v88, v89
	v_cvt_pk_bf16_f32 v70, v106, v107
	v_cvt_pk_bf16_f32 v71, v108, v109
	v_cvt_pk_bf16_f32 v72, v78, v79
	v_cvt_pk_bf16_f32 v73, v80, v81
	s_waitcnt lgkmcnt(0)
	v_mfma_f32_32x32x16_bf16 v[2:17], v[66:69], v[102:105], v[2:17]
	v_mfma_f32_32x32x16_bf16 v[34:49], v[74:77], v[70:73], v[34:49]
	v_add_f32_e32 v74, v82, v83
	v_add_f32_e32 v75, v84, v85
	v_add_f32_e64 v74, v86, v74
	v_add_f32_e64 v75, v87, v75
	v_add_f32_e64 v74, v90, v74
	v_add_f32_e64 v75, v91, v75
	v_add_f32_e32 v74, v74, v75
	v_mfma_f32_32x32x16_bf16 v[50:65], v[66:69], v[70:73], v[50:65]
	v_add_f32_e32 v159, v159, v74

.LBB0_1757:
	v_exp_f32_e32 v168, v86
	v_exp_f32_e32 v86, v70
	v_exp_f32_e32 v169, v87
	v_exp_f32_e32 v87, v71
	v_exp_f32_e32 v170, v88
	v_exp_f32_e32 v88, v72
	v_exp_f32_e32 v171, v89
	v_exp_f32_e32 v89, v73
	v_exp_f32_e32 v90, v90
	v_exp_f32_e32 v70, v74
	v_exp_f32_e32 v91, v91
	v_exp_f32_e32 v92, v92
	v_exp_f32_e32 v72, v76
	v_exp_f32_e32 v93, v93
	v_exp_f32_e32 v73, v77
	v_exp_f32_e32 v71, v75
	v_exp_f32_e32 v164, v82
	v_exp_f32_e32 v82, v66
	v_exp_f32_e32 v165, v83
	v_exp_f32_e32 v83, v67
	v_exp_f32_e32 v166, v84
	v_exp_f32_e32 v84, v68
	v_exp_f32_e32 v167, v85
	v_exp_f32_e32 v85, v69
	v_exp_f32_e32 v162, v94
	v_exp_f32_e32 v66, v78
	v_exp_f32_e32 v163, v95
	v_exp_f32_e32 v94, v96
	v_exp_f32_e32 v68, v80
	v_exp_f32_e32 v95, v97
	v_exp_f32_e32 v69, v81
	v_exp_f32_e32 v67, v79
	v_add_f32_e32 v76, v72, v92
	v_add_f32_e32 v77, v73, v93
	v_add_f32_e32 v80, v70, v90
	v_add_f32_e32 v81, v71, v91
	v_add_f32_e32 v96, v88, v170
	v_add_f32_e32 v97, v89, v171
	v_add_f32_e32 v176, v86, v168
	v_add_f32_e32 v177, v87, v169
	v_add_f32_e32 v78, v68, v94
	v_add_f32_e32 v79, v69, v95
	v_add_f32_e32 v74, v66, v162
	v_add_f32_e32 v75, v67, v163
	v_add_f32_e32 v178, v84, v166
	v_add_f32_e32 v179, v85, v167
	v_add_f32_e32 v180, v82, v164
	v_add_f32_e32 v181, v83, v165
	v_add_f32_e32 v176, v176, v177
	v_add_f32_e32 v96, v96, v97
	v_add_f32_e32 v80, v80, v81
	v_add_f32_e32 v76, v76, v77
	v_add_f32_e32 v180, v180, v181
	v_add_f32_e32 v178, v178, v179
	v_add_f32_e32 v96, v176, v96
	v_add_f32_e32 v97, v80, v76
	v_add_f32_e32 v80, v74, v75
	v_add3_u32 v176, s12, v187, v188
	v_add_f32_e32 v78, v78, v79
	v_add_f32_e32 v178, v180, v178
	ds_read_b64_tr_b16 v[74:75], v176 offset:18432
	ds_read_b64_tr_b16 v[76:77], v176 offset:19584
	v_add_f32_e32 v177, v80, v78
	v_cvt_pk_bf16_f32 v78, v164, v165
	v_cvt_pk_bf16_f32 v79, v166, v167
	ds_read_b64_tr_b16 v[166:167], v176 offset:19648
	ds_read_b64_tr_b16 v[164:165], v176 offset:18496
	v_cvt_pk_bf16_f32 v80, v168, v169
	v_add_f32_e32 v168, v178, v96
	v_add_f32_e32 v169, v97, v177
	v_exp_f32_e32 v96, v114
	v_exp_f32_e32 v97, v115
	v_exp_f32_e32 v114, v116
	v_exp_f32_e32 v115, v117
	v_exp_f32_e32 v116, v118
	v_exp_f32_e32 v117, v119
	v_exp_f32_e32 v118, v120
	v_exp_f32_e32 v119, v121
	v_cvt_pk_bf16_f32 v81, v170, v171
	v_exp_f32_e32 v120, v128
	v_exp_f32_e32 v121, v129
	s_waitcnt lgkmcnt(2)
	v_mfma_f32_32x32x16_bf16 v[34:49], v[74:77], v[78:81], v[34:49]
	v_cvt_pk_bf16_f32 v70, v70, v71
	v_cvt_pk_bf16_f32 v71, v72, v73
	v_cvt_pk_bf16_f32 v72, v66, v67
	v_cvt_pk_bf16_f32 v73, v68, v69
	s_waitcnt lgkmcnt(0)
	v_mfma_f32_32x32x16_bf16 v[2:17], v[164:167], v[78:81], v[2:17]
	v_cvt_pk_bf16_f32 v78, v96, v97
	v_cvt_pk_bf16_f32 v79, v114, v115
	v_cvt_pk_bf16_f32 v80, v116, v117
	v_cvt_pk_bf16_f32 v81, v118, v119
	s_nop 1
	v_mfma_f32_32x32x16_bf16 v[18:33], v[74:77], v[78:81], v[18:33]
	v_add_f32_e32 v74, v168, v169
	v_add_f32_e32 v189, v189, v74
	v_cvt_pk_bf16_f32 v74, v90, v91
	v_cvt_pk_bf16_f32 v75, v92, v93
	ds_read_b64_tr_b16 v[90:91], v176 offset:20736
	ds_read_b64_tr_b16 v[92:93], v176 offset:21888
	v_cvt_pk_bf16_f32 v77, v94, v95
	v_exp_f32_e32 v94, v126
	v_mfma_f32_32x32x16_bf16 v[50:65], v[164:167], v[78:81], v[50:65]
	v_cvt_pk_bf16_f32 v78, v82, v83
	v_cvt_pk_bf16_f32 v79, v84, v85
	ds_read_b64_tr_b16 v[84:85], v176 offset:21952
	ds_read_b64_tr_b16 v[82:83], v176 offset:20800
	v_cvt_pk_bf16_f32 v80, v86, v87
	v_cvt_pk_bf16_f32 v81, v88, v89
	v_exp_f32_e32 v86, v122
	v_exp_f32_e32 v87, v123
	v_exp_f32_e32 v88, v124
	v_exp_f32_e32 v89, v125
	v_exp_f32_e32 v95, v127
	v_cvt_pk_bf16_f32 v76, v162, v163
	ds_read_b64_tr_b16 v[66:67], v176 offset:23040
	ds_read_b64_tr_b16 v[68:69], v176 offset:24192
	s_waitcnt lgkmcnt(4)
	v_mfma_f32_32x32x16_bf16 v[34:49], v[90:93], v[74:77], v[34:49]
	s_waitcnt lgkmcnt(2)
	v_mfma_f32_32x32x16_bf16 v[2:17], v[82:85], v[74:77], v[2:17]
	v_cvt_pk_bf16_f32 v74, v86, v87
	v_cvt_pk_bf16_f32 v75, v88, v89
	v_cvt_pk_bf16_f32 v76, v94, v95
	v_cvt_pk_bf16_f32 v77, v120, v121
	s_nop 1
	v_mfma_f32_32x32x16_bf16 v[18:33], v[90:93], v[74:77], v[18:33]
	v_exp_f32_e32 v90, v98
	v_exp_f32_e32 v91, v99
	v_exp_f32_e32 v92, v100
	v_exp_f32_e32 v93, v101
	v_exp_f32_e32 v98, v106
	v_exp_f32_e32 v99, v107
	v_exp_f32_e32 v100, v108
	v_mfma_f32_32x32x16_bf16 v[50:65], v[82:85], v[74:77], v[50:65]
	ds_read_b64_tr_b16 v[76:77], v176 offset:24256
	ds_read_b64_tr_b16 v[74:75], v176 offset:23104
	v_exp_f32_e32 v82, v102
	v_exp_f32_e32 v83, v103
	v_exp_f32_e32 v84, v104
	v_exp_f32_e32 v85, v105
	v_exp_f32_e32 v101, v109
	v_exp_f32_e32 v102, v110
	s_waitcnt lgkmcnt(2)
	v_mfma_f32_32x32x16_bf16 v[34:49], v[66:69], v[78:81], v[34:49]
	v_exp_f32_e32 v104, v112
	v_exp_f32_e32 v105, v113
	v_exp_f32_e32 v103, v111
	v_add_f32_e32 v88, v100, v88
	v_add_f32_e32 v89, v101, v89
	v_add_f32_e32 v106, v84, v118
	v_add_f32_e32 v107, v85, v119
	v_add_f32_e32 v108, v104, v120
	v_add_f32_e32 v109, v105, v121
	s_waitcnt lgkmcnt(0)
	v_mfma_f32_32x32x16_bf16 v[2:17], v[74:77], v[78:81], v[2:17]
	v_cvt_pk_bf16_f32 v78, v90, v91
	v_cvt_pk_bf16_f32 v79, v92, v93
	v_cvt_pk_bf16_f32 v80, v82, v83
	v_cvt_pk_bf16_f32 v81, v84, v85
	v_add_f32_e64 v90, v90, v96
	v_add_f32_e64 v91, v91, v97
	v_add_f32_e32 v92, v92, v114
	v_add_f32_e32 v93, v93, v115
	v_add_f32_e32 v82, v82, v116
	v_add_f32_e32 v83, v83, v117
	v_mfma_f32_32x32x16_bf16 v[18:33], v[66:69], v[78:81], v[18:33]
	ds_read_b64_tr_b16 v[66:67], v176 offset:25344
	ds_read_b64_tr_b16 v[68:69], v176 offset:26496
	v_add_f32_e64 v84, v102, v94
	v_add_f32_e64 v85, v103, v95
	v_mfma_f32_32x32x16_bf16 v[50:65], v[74:77], v[78:81], v[50:65]
	v_add_f32_e64 v74, v98, v86
	v_add_f32_e64 v75, v99, v87
	v_add_f32_e32 v79, v74, v75
	v_add_f32_e32 v78, v90, v91
	ds_read_b64_tr_b16 v[76:77], v176 offset:26560
	ds_read_b64_tr_b16 v[74:75], v176 offset:25408
	v_mov_b32_e32 v80, v92
	s_waitcnt lgkmcnt(2)
	v_mfma_f32_32x32x16_bf16 v[34:49], v[66:69], v[70:73], v[34:49]
	v_mov_b32_e32 v81, v88
	v_mov_b32_e32 v88, v93
	v_add_f32_e64 v80, v80, v88
	v_add_f32_e64 v81, v81, v89
	v_add_f32_e64 v78, v78, v80
	v_add_f32_e64 v79, v79, v81
	v_mov_b32_e32 v80, v82
	v_mov_b32_e32 v81, v84
	s_waitcnt lgkmcnt(0)
	v_mfma_f32_32x32x16_bf16 v[2:17], v[74:77], v[70:73], v[2:17]
	v_cvt_pk_bf16_f32 v70, v98, v99
	v_cvt_pk_bf16_f32 v71, v100, v101
	v_cvt_pk_bf16_f32 v72, v102, v103
	v_cvt_pk_bf16_f32 v73, v104, v105
	v_mov_b32_e32 v84, v83
	v_mov_b32_e32 v82, v106
	v_mov_b32_e32 v83, v108
	v_mfma_f32_32x32x16_bf16 v[18:33], v[66:69], v[70:73], v[18:33]
	v_mov_b32_e32 v108, v107
	v_add_f32_e64 v80, v80, v84
	v_add_f32_e64 v81, v81, v85
	v_add_f32_e64 v66, v82, v108
	v_add_f32_e64 v67, v83, v109
	v_add_f32_e32 v66, v80, v66
	v_add_f32_e32 v67, v81, v67
	s_nop 0
	v_add_f32_e32 v66, v78, v66
	v_add_f32_e32 v67, v79, v67
	v_mfma_f32_32x32x16_bf16 v[50:65], v[74:77], v[70:73], v[50:65]
	v_add_f32_e32 v66, v66, v67
	v_add_f32_e32 v159, v159, v66

.Lcp_loop:
	s_waitcnt vmcnt(8)
	v_lshlrev_b32_e32 v64, 16, v52
	v_and_b32_e32 v65, 0xffff0000, v52
	v_add_f32_e32 v56, v56, v64
	v_add_f32_e32 v57, v57, v65
	v_lshlrev_b32_e32 v66, 16, v53
	v_and_b32_e32 v67, 0xffff0000, v53
	v_add_f32_e32 v58, v58, v66
	v_add_f32_e32 v59, v59, v67
	v_lshlrev_b32_e32 v64, 16, v54
	v_and_b32_e32 v65, 0xffff0000, v54
	v_add_f32_e32 v60, v60, v64
	v_add_f32_e32 v61, v61, v65
	v_lshlrev_b32_e32 v66, 16, v55
	v_and_b32_e32 v67, 0xffff0000, v55
	v_add_f32_e32 v62, v62, v66
	v_add_f32_e32 v63, v63, v67
	v_cvt_pk_bf16_f32 v52, v56, v57
	v_cvt_pk_bf16_f32 v53, v58, v59
	v_cvt_pk_bf16_f32 v54, v60, v61
	v_cvt_pk_bf16_f32 v55, v62, v63
	ds_write_b128 v164, v[52:55]
	s_waitcnt vmcnt(7)
	ds_write_b128 v166, v[68:71]
	s_waitcnt vmcnt(6)
	ds_write_b128 v166, v[72:75] offset:1088
	s_waitcnt vmcnt(5)
	ds_write_b128 v166, v[76:79] offset:2176
	s_waitcnt vmcnt(4)
	ds_write_b128 v166, v[80:83] offset:3264
	s_waitcnt vmcnt(3)
	ds_write_b128 v166, v[84:87] offset:4352
	s_waitcnt vmcnt(2)
	ds_write_b128 v166, v[88:91] offset:5440
	s_waitcnt vmcnt(1)
	ds_write_b128 v166, v[92:95] offset:6528
	s_waitcnt vmcnt(0)
	ds_write_b128 v166, v[96:99] offset:7616
	s_waitcnt lgkmcnt(0)
	s_barrier
	s_cmpk_eq_i32 s6, 0x2000
	s_cbranch_scc1 .Lcp_noload0
	v_add_u32_e32 v0, s101, v40
	v_min_u32_e32 v0, 0x1fff, v0
	v_mul_u32_u24_e32 v0, 0xb00, v0
	v_lshlrev_b32_e32 v0, 1, v0
	v_lshl_add_u64 v[20:21], v[180:181], 0, v[0:1]
	global_load_dwordx4 v[52:55], v[20:21], off
	v_lshl_add_u64 v[18:19], v[182:183], 0, s[6:7]
	global_load_dwordx4 v[56:59], v[18:19], off
	global_load_dwordx4 v[60:63], v[18:19], off offset:16
	global_load_dwordx4 v[68:71], v168, s[20:21]
	global_load_dwordx4 v[72:75], v169, s[20:21]
	global_load_dwordx4 v[76:79], v170, s[20:21]
	global_load_dwordx4 v[80:83], v171, s[20:21]
	global_load_dwordx4 v[84:87], v176, s[20:21]
	global_load_dwordx4 v[88:91], v177, s[20:21]
	global_load_dwordx4 v[92:95], v178, s[20:21]
	global_load_dwordx4 v[96:99], v179, s[20:21]
	s_add_u32 s6, s6, 0x200
	s_addc_u32 s7, s7, 0
	v_add_u32_e32 v40, 2, v40
	s_add_u32 s20, s20, 0x100
	s_addc_u32 s21, s21, 0
.Lcp_noload0:
	ds_read_b128 v[100:103], v165
	ds_read_b128 v[132:135], v167
	ds_read_b128 v[104:107], v165 offset:1024
	ds_read_b128 v[136:139], v167 offset:32
	ds_read_b128 v[108:111], v165 offset:2048
	ds_read_b128 v[140:143], v167 offset:64
	ds_read_b128 v[112:115], v165 offset:3072
	ds_read_b128 v[144:147], v167 offset:96
	ds_read_b128 v[116:119], v165 offset:4096
	ds_read_b128 v[148:151], v167 offset:128
	ds_read_b128 v[120:123], v165 offset:5120
	ds_read_b128 v[152:155], v167 offset:160
	ds_read_b128 v[124:127], v165 offset:6144
	ds_read_b128 v[156:159], v167 offset:192
	s_waitcnt lgkmcnt(12)
	v_mfma_f32_32x32x16_bf16 v[2:17], v[100:103], v[132:135], v[2:17]
	ds_read_b128 v[128:131], v165 offset:7168
	ds_read_b128 v[160:163], v167 offset:224
	s_waitcnt lgkmcnt(12)
	v_mfma_f32_32x32x16_bf16 v[2:17], v[104:107], v[136:139], v[2:17]
	s_waitcnt lgkmcnt(10)
	v_mfma_f32_32x32x16_bf16 v[2:17], v[108:111], v[140:143], v[2:17]
	s_waitcnt lgkmcnt(8)
	v_mfma_f32_32x32x16_bf16 v[2:17], v[112:115], v[144:147], v[2:17]
	s_waitcnt lgkmcnt(6)
	v_mfma_f32_32x32x16_bf16 v[2:17], v[116:119], v[148:151], v[2:17]
	s_waitcnt lgkmcnt(4)
	v_mfma_f32_32x32x16_bf16 v[2:17], v[120:123], v[152:155], v[2:17]
	s_waitcnt lgkmcnt(2)
	v_mfma_f32_32x32x16_bf16 v[2:17], v[124:127], v[156:159], v[2:17]
	s_waitcnt lgkmcnt(0)
	v_mfma_f32_32x32x16_bf16 v[2:17], v[128:131], v[160:163], v[2:17]
	s_sub_i32 vcc_lo, vcc_lo, 1
	s_waitcnt vmcnt(8)
	v_lshlrev_b32_e32 v64, 16, v52
	v_and_b32_e32 v65, 0xffff0000, v52
	v_add_f32_e32 v56, v56, v64
	v_add_f32_e32 v57, v57, v65
	v_lshlrev_b32_e32 v66, 16, v53
	v_and_b32_e32 v67, 0xffff0000, v53
	v_add_f32_e32 v58, v58, v66
	v_add_f32_e32 v59, v59, v67
	v_lshlrev_b32_e32 v64, 16, v54
	v_and_b32_e32 v65, 0xffff0000, v54
	v_add_f32_e32 v60, v60, v64
	v_add_f32_e32 v61, v61, v65
	v_lshlrev_b32_e32 v66, 16, v55
	v_and_b32_e32 v67, 0xffff0000, v55
	v_add_f32_e32 v62, v62, v66
	v_add_f32_e32 v63, v63, v67
	v_cvt_pk_bf16_f32 v52, v56, v57
	v_cvt_pk_bf16_f32 v53, v58, v59
	v_cvt_pk_bf16_f32 v54, v60, v61
	v_cvt_pk_bf16_f32 v55, v62, v63
	ds_write_b128 v164, v[52:55] offset:8192
	s_waitcnt vmcnt(7)
	ds_write_b128 v166, v[68:71]
	s_waitcnt vmcnt(6)
	ds_write_b128 v166, v[72:75] offset:1088
	s_waitcnt vmcnt(5)
	ds_write_b128 v166, v[76:79] offset:2176
	s_waitcnt vmcnt(4)
	ds_write_b128 v166, v[80:83] offset:3264
	s_waitcnt vmcnt(3)
	ds_write_b128 v166, v[84:87] offset:4352
	s_waitcnt vmcnt(2)
	ds_write_b128 v166, v[88:91] offset:5440
	s_waitcnt vmcnt(1)
	ds_write_b128 v166, v[92:95] offset:6528
	s_waitcnt vmcnt(0)
	ds_write_b128 v166, v[96:99] offset:7616
	s_waitcnt lgkmcnt(0)
	s_barrier
	s_cmpk_eq_i32 s6, 0x2000
	s_cbranch_scc1 .Lcp_noload1
	v_add_u32_e32 v0, s101, v40
	v_min_u32_e32 v0, 0x1fff, v0
	v_mul_u32_u24_e32 v0, 0xb00, v0
	v_lshlrev_b32_e32 v0, 1, v0
	v_lshl_add_u64 v[20:21], v[180:181], 0, v[0:1]
	global_load_dwordx4 v[52:55], v[20:21], off
	v_lshl_add_u64 v[18:19], v[182:183], 0, s[6:7]
	global_load_dwordx4 v[56:59], v[18:19], off
	global_load_dwordx4 v[60:63], v[18:19], off offset:16
	global_load_dwordx4 v[68:71], v168, s[20:21]
	global_load_dwordx4 v[72:75], v169, s[20:21]
	global_load_dwordx4 v[76:79], v170, s[20:21]
	global_load_dwordx4 v[80:83], v171, s[20:21]
	global_load_dwordx4 v[84:87], v176, s[20:21]
	global_load_dwordx4 v[88:91], v177, s[20:21]
	global_load_dwordx4 v[92:95], v178, s[20:21]
	global_load_dwordx4 v[96:99], v179, s[20:21]
	s_add_u32 s6, s6, 0x200
	s_addc_u32 s7, s7, 0
	v_add_u32_e32 v40, 2, v40
	s_add_u32 s20, s20, 0x100
	s_addc_u32 s21, s21, 0
